# attention fast loops: the next tile's V^T fragment reads move from the softmax segment head into the K.Q^T MFMA shadows of the previous MFMA segment (slot freed by each MFMA), MFMA segment closes with
# speedup vs baseline: 1.0208x; 1.0133x over previous
.Lfm_entry:
	s_mov_b32 s60, s58
	s_mov_b32 s58, s0
	v_add_u32_e32 v248, s58, v160
	ds_read_b128 v[164:167], v248 offset:13312
	ds_read_b128 v[168:171], v248 offset:17920
	ds_read_b128 v[172:175], v248 offset:13344
	ds_read_b128 v[176:179], v248 offset:17952
	ds_read_b128 v[180:183], v248 offset:13376
	ds_read_b128 v[220:223], v248 offset:17984
	ds_read_b128 v[224:227], v248 offset:13408
	ds_read_b128 v[232:235], v248 offset:18016

.Lfm_a_exp:
	v_exp_f32_e32 v34, v34
	v_exp_f32_e32 v50, v50
	v_exp_f32_e32 v35, v35
	v_exp_f32_e32 v51, v51
	v_exp_f32_e32 v42, v42
	v_exp_f32_e32 v58, v58
	v_exp_f32_e32 v43, v43
	v_exp_f32_e32 v59, v59
	v_exp_f32_e32 v36, v36
	v_exp_f32_e32 v52, v52
	v_exp_f32_e32 v37, v37
	v_exp_f32_e32 v53, v53
	v_exp_f32_e32 v44, v44
	v_exp_f32_e32 v60, v60
	v_exp_f32_e32 v45, v45
	v_exp_f32_e32 v61, v61
	v_exp_f32_e32 v38, v38
	v_exp_f32_e32 v54, v54
	v_exp_f32_e32 v39, v39
	v_exp_f32_e32 v55, v55
	v_exp_f32_e32 v46, v46
	v_exp_f32_e32 v62, v62
	v_exp_f32_e32 v47, v47
	v_exp_f32_e32 v63, v63
	v_exp_f32_e32 v40, v40
	v_exp_f32_e32 v56, v56
	v_exp_f32_e32 v41, v41
	v_exp_f32_e32 v57, v57
	v_exp_f32_e32 v48, v48
	v_exp_f32_e32 v64, v64
	v_exp_f32_e32 v49, v49
	v_exp_f32_e32 v65, v65
	v_pk_add_f32 v[122:123], v[34:35], v[50:51]
	v_pk_add_f32 v[124:125], v[36:37], v[52:53]
	v_pk_add_f32 v[126:127], v[38:39], v[54:55]
	v_pk_add_f32 v[128:129], v[40:41], v[56:57]
	v_pk_add_f32 v[130:131], v[42:43], v[58:59]
	v_pk_add_f32 v[132:133], v[44:45], v[60:61]
	v_pk_add_f32 v[134:135], v[46:47], v[62:63]
	v_pk_add_f32 v[136:137], v[48:49], v[64:65]
	v_pk_add_f32 v[122:123], v[122:123], v[124:125]
	v_pk_add_f32 v[126:127], v[126:127], v[128:129]
	v_pk_add_f32 v[130:131], v[130:131], v[132:133]
	v_pk_add_f32 v[134:135], v[134:135], v[136:137]
	v_pk_add_f32 v[122:123], v[122:123], v[126:127]
	v_pk_add_f32 v[130:131], v[130:131], v[134:135]
	v_pk_add_f32 v[122:123], v[122:123], v[130:131]
	v_add_f32_e32 v0, v122, v123
	v_cvt_pk_bf16_f32 v122, v34, v35
	v_cvt_pk_bf16_f32 v123, v36, v37
	v_cvt_pk_bf16_f32 v124, v38, v39
	v_cvt_pk_bf16_f32 v125, v40, v41
	v_cvt_pk_bf16_f32 v126, v42, v43
	v_cvt_pk_bf16_f32 v127, v44, v45
	v_cvt_pk_bf16_f32 v128, v46, v47
	v_cvt_pk_bf16_f32 v129, v48, v49
	v_cvt_pk_bf16_f32 v130, v50, v51
	v_cvt_pk_bf16_f32 v131, v52, v53
	v_cvt_pk_bf16_f32 v132, v54, v55
	v_cvt_pk_bf16_f32 v133, v56, v57
	v_cvt_pk_bf16_f32 v134, v58, v59
	v_cvt_pk_bf16_f32 v135, v60, v61
	v_cvt_pk_bf16_f32 v136, v62, v63
	v_cvt_pk_bf16_f32 v137, v64, v65
	v_add_f32_e32 v162, v162, v0
	s_waitcnt lgkmcnt(0)
	s_barrier
	v_mfma_f32_32x32x16_bf16 v[2:17], v[164:167], v[122:125], v[2:17]
	s_setprio 1
	v_add3_u32 v0, s57, v152, v153
	s_waitcnt vmcnt(4)
	ds_write_b128 v0, v[86:89]
	v_mfma_f32_32x32x16_bf16 v[18:33], v[168:171], v[122:125], v[18:33]
	v_add3_u32 v0, s57, v154, v155
	s_waitcnt vmcnt(3)
	ds_write_b128 v0, v[90:93]
	v_mfma_f32_32x32x16_bf16 v[2:17], v[172:175], v[126:129], v[2:17]
	v_add3_u32 v0, s57, v156, v140
	ds_write_b128 v0, v[82:85] offset:13312
	v_add_u32_e32 v249, s60, v157
	v_mfma_f32_32x32x16_bf16 v[18:33], v[176:179], v[126:129], v[18:33]
	ds_read_b128 v[236:239], v249
	ds_read_b128 v[240:243], v249 offset:6656
	ds_read_b128 v[244:247], v249 offset:32
	v_mfma_f32_32x32x16_bf16 v[2:17], v[180:183], v[130:133], v[2:17]
	ds_read_b128 v[164:167], v249 offset:6688
	ds_read_b128 v[168:171], v249 offset:64
	ds_read_b128 v[172:175], v249 offset:6720
	v_mfma_f32_32x32x16_bf16 v[18:33], v[220:223], v[130:133], v[18:33]
	ds_read_b128 v[176:179], v249 offset:96
	ds_read_b128 v[180:183], v249 offset:6752
	ds_read_b128 v[220:223], v249 offset:128
	v_mfma_f32_32x32x16_bf16 v[2:17], v[224:227], v[134:137], v[2:17]
	ds_read_b128 v[224:227], v249 offset:6784
	v_mfma_f32_32x32x16_bf16 v[18:33], v[232:235], v[134:137], v[18:33]
	ds_read_b128 v[232:235], v249 offset:160
	s_waitcnt lgkmcnt(9)
	v_mfma_f32_32x32x16_bf16 v[34:49], v[236:239], v[196:199], v[66:81]
	ds_read_b128 v[236:239], v249 offset:6816
	s_add_i32 s0, s59, 4
	s_cmp_lt_u32 s59, s48
	v_mfma_f32_32x32x16_bf16 v[50:65], v[240:243], v[196:199], v[66:81]
	s_cselect_b32 s0, s0, s50
	s_lshl_b32 s8, s0, 6
	s_mul_i32 s0, s8, 0x600
	s_waitcnt lgkmcnt(7)
	v_mfma_f32_32x32x16_bf16 v[34:49], v[244:247], v[200:203], v[34:49]
	v_add_u32_e32 v248, s60, v160
	s_mov_b32 s1, 0
	v_lshl_add_u64 v[82:83], s[0:1], 0, v[186:187]
	v_lshl_add_u64 v[84:85], s[0:1], 0, v[188:189]
	v_mfma_f32_32x32x16_bf16 v[50:65], v[164:167], v[200:203], v[50:65]
	ds_read_b128 v[164:167], v248 offset:13312
	global_load_dwordx4 v[86:89], v[82:83], off
	global_load_dwordx4 v[90:93], v[84:85], off
	v_lshl_add_u64 v[82:83], s[8:9], 1, v[142:143]
	v_mfma_f32_32x32x16_bf16 v[34:49], v[168:171], v[204:207], v[34:49]
	ds_read_b128 v[168:171], v248 offset:17920
	global_load_dwordx4 v[82:85], v[82:83], off
	s_waitcnt lgkmcnt(6)
	v_mfma_f32_32x32x16_bf16 v[50:65], v[172:175], v[204:207], v[50:65]
	ds_read_b128 v[172:175], v248 offset:13344
	v_mfma_f32_32x32x16_bf16 v[34:49], v[176:179], v[208:211], v[34:49]
	ds_read_b128 v[176:179], v248 offset:17952
	v_mfma_f32_32x32x16_bf16 v[50:65], v[180:183], v[208:211], v[50:65]
	ds_read_b128 v[180:183], v248 offset:13376
	s_waitcnt lgkmcnt(6)
	v_mfma_f32_32x32x16_bf16 v[34:49], v[220:223], v[212:215], v[34:49]
	ds_read_b128 v[220:223], v248 offset:17984
	v_mfma_f32_32x32x16_bf16 v[50:65], v[224:227], v[212:215], v[50:65]
	ds_read_b128 v[224:227], v248 offset:13408
	v_mfma_f32_32x32x16_bf16 v[34:49], v[232:235], v[216:219], v[34:49]
	ds_read_b128 v[232:235], v248 offset:18016
	s_waitcnt lgkmcnt(8)
	v_mfma_f32_32x32x16_bf16 v[50:65], v[236:239], v[216:219], v[50:65]
	s_setprio 0
	s_waitcnt lgkmcnt(8)
	s_barrier
	v_max3_f32 v0, v34, v35, v36
	v_max3_f32 v106, v50, v51, v52
	v_max3_f32 v0, v0, v37, v38
	v_max3_f32 v106, v106, v53, v54
	v_max3_f32 v0, v0, v39, v40
	v_max3_f32 v106, v106, v55, v56
	v_max3_f32 v0, v0, v41, v42
	v_max3_f32 v106, v106, v57, v58
	v_max3_f32 v0, v0, v43, v44
	v_max3_f32 v106, v106, v59, v60
	v_max3_f32 v0, v0, v45, v46
	v_max3_f32 v106, v106, v61, v62
	v_max_f32_e32 v107, v65, v65
	v_max_f32_e32 v108, v49, v49
	v_max3_f32 v0, v0, v47, v48
	v_max3_f32 v106, v106, v63, v64
	v_max_f32_e32 v107, v108, v107
	v_max3_f32 v0, v0, v106, v107
	v_cmp_lt_f32_e32 vcc, s35, v0
	s_cbranch_vccnz .Lfm_b_resc
.Lfm_b_exp:
	v_exp_f32_e32 v34, v34
	v_exp_f32_e32 v50, v50
	v_exp_f32_e32 v35, v35
	v_exp_f32_e32 v51, v51
	v_exp_f32_e32 v42, v42
	v_exp_f32_e32 v58, v58
	v_exp_f32_e32 v43, v43
	v_exp_f32_e32 v59, v59
	v_exp_f32_e32 v36, v36
	v_exp_f32_e32 v52, v52
	v_exp_f32_e32 v37, v37
	v_exp_f32_e32 v53, v53
	v_exp_f32_e32 v44, v44
	v_exp_f32_e32 v60, v60
	v_exp_f32_e32 v45, v45
	v_exp_f32_e32 v61, v61
	v_exp_f32_e32 v38, v38
	v_exp_f32_e32 v54, v54
	v_exp_f32_e32 v39, v39
	v_exp_f32_e32 v55, v55
	v_exp_f32_e32 v46, v46
	v_exp_f32_e32 v62, v62
	v_exp_f32_e32 v47, v47
	v_exp_f32_e32 v63, v63
	v_exp_f32_e32 v40, v40
	v_exp_f32_e32 v56, v56
	v_exp_f32_e32 v41, v41
	v_exp_f32_e32 v57, v57
	v_exp_f32_e32 v48, v48
	v_exp_f32_e32 v64, v64
	v_exp_f32_e32 v49, v49
	v_exp_f32_e32 v65, v65
	v_pk_add_f32 v[106:107], v[34:35], v[50:51]
	v_pk_add_f32 v[108:109], v[36:37], v[52:53]
	v_pk_add_f32 v[110:111], v[38:39], v[54:55]
	v_pk_add_f32 v[112:113], v[40:41], v[56:57]
	v_pk_add_f32 v[114:115], v[42:43], v[58:59]
	v_pk_add_f32 v[116:117], v[44:45], v[60:61]
	v_pk_add_f32 v[118:119], v[46:47], v[62:63]
	v_pk_add_f32 v[120:121], v[48:49], v[64:65]
	v_pk_add_f32 v[106:107], v[106:107], v[108:109]
	v_pk_add_f32 v[110:111], v[110:111], v[112:113]
	v_pk_add_f32 v[114:115], v[114:115], v[116:117]
	v_pk_add_f32 v[118:119], v[118:119], v[120:121]
	v_pk_add_f32 v[106:107], v[106:107], v[110:111]
	v_pk_add_f32 v[114:115], v[114:115], v[118:119]
	v_pk_add_f32 v[106:107], v[106:107], v[114:115]
	v_add_f32_e32 v0, v106, v107
	v_cvt_pk_bf16_f32 v106, v34, v35
	v_cvt_pk_bf16_f32 v107, v36, v37
	v_cvt_pk_bf16_f32 v108, v38, v39
	v_cvt_pk_bf16_f32 v109, v40, v41
	v_cvt_pk_bf16_f32 v110, v42, v43
	v_cvt_pk_bf16_f32 v111, v44, v45
	v_cvt_pk_bf16_f32 v112, v46, v47
	v_cvt_pk_bf16_f32 v113, v48, v49
	v_cvt_pk_bf16_f32 v114, v50, v51
	v_cvt_pk_bf16_f32 v115, v52, v53
	v_cvt_pk_bf16_f32 v116, v54, v55
	v_cvt_pk_bf16_f32 v117, v56, v57
	v_cvt_pk_bf16_f32 v118, v58, v59
	v_cvt_pk_bf16_f32 v119, v60, v61
	v_cvt_pk_bf16_f32 v120, v62, v63
	v_cvt_pk_bf16_f32 v121, v64, v65
	v_add_f32_e32 v162, v162, v0
	s_waitcnt lgkmcnt(0)
	s_barrier
	v_mfma_f32_32x32x16_bf16 v[2:17], v[164:167], v[106:109], v[2:17]
	s_setprio 1
	v_add3_u32 v0, s58, v152, v153
	s_waitcnt vmcnt(5)
	ds_write_b128 v0, v[98:101]
	v_mfma_f32_32x32x16_bf16 v[18:33], v[168:171], v[106:109], v[18:33]
	v_add3_u32 v0, s58, v154, v155
	s_waitcnt vmcnt(4)
	ds_write_b128 v0, v[94:97]
	v_mfma_f32_32x32x16_bf16 v[2:17], v[172:175], v[110:113], v[2:17]
	v_add3_u32 v0, s58, v156, v140
	s_waitcnt vmcnt(3)
	ds_write_b128 v0, v[102:105] offset:13312
	v_add_u32_e32 v249, s57, v157
	v_mfma_f32_32x32x16_bf16 v[18:33], v[176:179], v[110:113], v[18:33]
	ds_read_b128 v[236:239], v249
	ds_read_b128 v[240:243], v249 offset:6656
	ds_read_b128 v[244:247], v249 offset:32
	v_mfma_f32_32x32x16_bf16 v[2:17], v[180:183], v[114:117], v[2:17]
	ds_read_b128 v[164:167], v249 offset:6688
	ds_read_b128 v[168:171], v249 offset:64
	ds_read_b128 v[172:175], v249 offset:6720
	v_mfma_f32_32x32x16_bf16 v[18:33], v[220:223], v[114:117], v[18:33]
	ds_read_b128 v[176:179], v249 offset:96
	ds_read_b128 v[180:183], v249 offset:6752
	ds_read_b128 v[220:223], v249 offset:128
	v_mfma_f32_32x32x16_bf16 v[2:17], v[224:227], v[118:121], v[2:17]
	ds_read_b128 v[224:227], v249 offset:6784
	s_add_i32 s59, s59, 2
	s_mov_b32 s0, s58
	v_mfma_f32_32x32x16_bf16 v[18:33], v[232:235], v[118:121], v[18:33]
	ds_read_b128 v[232:235], v249 offset:160
	s_mov_b32 s58, s57
	s_mov_b32 s57, s60
	s_mov_b32 s60, s0
	s_addk_i32 s54, 0x80
	s_waitcnt lgkmcnt(9)
	v_mfma_f32_32x32x16_bf16 v[34:49], v[236:239], v[196:199], v[66:81]
	ds_read_b128 v[236:239], v249 offset:6816
	s_add_i32 s1, s59, 3
	s_cmp_lt_u32 s1, s49
	v_mfma_f32_32x32x16_bf16 v[50:65], v[240:243], v[196:199], v[66:81]
	s_cselect_b32 s1, s1, s50
	s_lshl_b32 s8, s1, 6
	s_mul_i32 s20, s8, 0x600
	s_waitcnt lgkmcnt(7)
	v_mfma_f32_32x32x16_bf16 v[34:49], v[244:247], v[200:203], v[34:49]
	v_add_u32_e32 v248, s58, v160
	s_mov_b32 s21, 0
	v_lshl_add_u64 v[94:95], s[20:21], 0, v[186:187]
	v_lshl_add_u64 v[96:97], s[20:21], 0, v[188:189]
	v_mfma_f32_32x32x16_bf16 v[50:65], v[164:167], v[200:203], v[50:65]
	ds_read_b128 v[164:167], v248 offset:13312
	v_lshl_add_u64 v[102:103], s[8:9], 1, v[142:143]
	global_load_dwordx4 v[98:101], v[94:95], off
	s_nop 0
	v_mfma_f32_32x32x16_bf16 v[34:49], v[168:171], v[204:207], v[34:49]
	ds_read_b128 v[168:171], v248 offset:17920
	global_load_dwordx4 v[94:97], v[96:97], off
	global_load_dwordx4 v[102:105], v[102:103], off
	s_waitcnt lgkmcnt(6)
	v_mfma_f32_32x32x16_bf16 v[50:65], v[172:175], v[204:207], v[50:65]
	ds_read_b128 v[172:175], v248 offset:13344
	v_mfma_f32_32x32x16_bf16 v[34:49], v[176:179], v[208:211], v[34:49]
	ds_read_b128 v[176:179], v248 offset:17952
	v_mfma_f32_32x32x16_bf16 v[50:65], v[180:183], v[208:211], v[50:65]
	ds_read_b128 v[180:183], v248 offset:13376
	s_waitcnt lgkmcnt(6)
	v_mfma_f32_32x32x16_bf16 v[34:49], v[220:223], v[212:215], v[34:49]
	ds_read_b128 v[220:223], v248 offset:17984
	v_mfma_f32_32x32x16_bf16 v[50:65], v[224:227], v[212:215], v[50:65]
	ds_read_b128 v[224:227], v248 offset:13408
	v_mfma_f32_32x32x16_bf16 v[34:49], v[232:235], v[216:219], v[34:49]
	ds_read_b128 v[232:235], v248 offset:18016
	s_waitcnt lgkmcnt(8)
	v_mfma_f32_32x32x16_bf16 v[50:65], v[236:239], v[216:219], v[50:65]
	s_setprio 0
	s_add_i32 s4, s55, s59
	s_cmp_lt_i32 s4, -2
	s_waitcnt lgkmcnt(8)
	s_barrier
	s_cbranch_scc1 .Lfm_head
	s_mov_b32 s0, s58
	s_mov_b32 s58, s60
	s_branch .LBB0_1037

.Lfd_entry:
	s_mov_b32 s55, s51
	s_mov_b32 s51, s0
	v_add_u32_e32 v248, s51, v190
	ds_read_b128 v[196:199], v248 offset:9216
	ds_read_b128 v[200:203], v248 offset:13824
	ds_read_b128 v[204:207], v248 offset:18432
	ds_read_b128 v[208:211], v248 offset:23040
	ds_read_b128 v[212:215], v248 offset:9248
	ds_read_b128 v[216:219], v248 offset:13856
	ds_read_b128 v[220:223], v248 offset:18464
	ds_read_b128 v[224:227], v248 offset:23072

.Lfd_a_exp:
	v_exp_f32_e32 v80, v80
	v_exp_f32_e32 v96, v96
	v_exp_f32_e32 v81, v81
	v_exp_f32_e32 v97, v97
	v_exp_f32_e32 v88, v88
	v_exp_f32_e32 v104, v104
	v_exp_f32_e32 v89, v89
	v_exp_f32_e32 v105, v105
	v_exp_f32_e32 v82, v82
	v_exp_f32_e32 v98, v98
	v_exp_f32_e32 v83, v83
	v_exp_f32_e32 v99, v99
	v_exp_f32_e32 v90, v90
	v_exp_f32_e32 v106, v106
	v_exp_f32_e32 v91, v91
	v_exp_f32_e32 v107, v107
	v_exp_f32_e32 v84, v84
	v_exp_f32_e32 v100, v100
	v_exp_f32_e32 v85, v85
	v_exp_f32_e32 v101, v101
	v_exp_f32_e32 v92, v92
	v_exp_f32_e32 v108, v108
	v_exp_f32_e32 v93, v93
	v_exp_f32_e32 v109, v109
	v_exp_f32_e32 v86, v86
	v_exp_f32_e32 v102, v102
	v_exp_f32_e32 v87, v87
	v_exp_f32_e32 v103, v103
	v_exp_f32_e32 v94, v94
	v_exp_f32_e32 v110, v110
	v_exp_f32_e32 v95, v95
	v_exp_f32_e32 v111, v111
	v_pk_add_f32 v[156:157], v[80:81], v[96:97]
	v_pk_add_f32 v[158:159], v[82:83], v[98:99]
	v_pk_add_f32 v[160:161], v[84:85], v[100:101]
	v_pk_add_f32 v[162:163], v[86:87], v[102:103]
	v_pk_add_f32 v[164:165], v[88:89], v[104:105]
	v_pk_add_f32 v[166:167], v[90:91], v[106:107]
	v_pk_add_f32 v[168:169], v[92:93], v[108:109]
	v_pk_add_f32 v[170:171], v[94:95], v[110:111]
	v_pk_add_f32 v[156:157], v[156:157], v[158:159]
	v_pk_add_f32 v[160:161], v[160:161], v[162:163]
	v_pk_add_f32 v[164:165], v[164:165], v[166:167]
	v_pk_add_f32 v[168:169], v[168:169], v[170:171]
	v_pk_add_f32 v[156:157], v[156:157], v[160:161]
	v_pk_add_f32 v[164:165], v[164:165], v[168:169]
	v_pk_add_f32 v[156:157], v[156:157], v[164:165]
	v_add_f32_e32 v0, v156, v157
	v_cvt_pk_bf16_f32 v156, v80, v81
	v_cvt_pk_bf16_f32 v157, v82, v83
	v_cvt_pk_bf16_f32 v158, v84, v85
	v_cvt_pk_bf16_f32 v159, v86, v87
	v_cvt_pk_bf16_f32 v160, v88, v89
	v_cvt_pk_bf16_f32 v161, v90, v91
	v_cvt_pk_bf16_f32 v162, v92, v93
	v_cvt_pk_bf16_f32 v163, v94, v95
	v_cvt_pk_bf16_f32 v164, v96, v97
	v_cvt_pk_bf16_f32 v165, v98, v99
	v_cvt_pk_bf16_f32 v166, v100, v101
	v_cvt_pk_bf16_f32 v167, v102, v103
	v_cvt_pk_bf16_f32 v168, v104, v105
	v_cvt_pk_bf16_f32 v169, v106, v107
	v_cvt_pk_bf16_f32 v170, v108, v109
	v_cvt_pk_bf16_f32 v171, v110, v111
	v_add_f32_e32 v193, v193, v0
	s_waitcnt lgkmcnt(0)
	s_barrier
	v_mfma_f32_32x32x16_bf16 v[64:79], v[196:199], v[156:159], v[64:79]
	s_setprio 1
	v_add_u32_e32 v14, s50, v188
	s_waitcnt vmcnt(3)
	ds_write_b128 v14, v[136:139]
	v_mfma_f32_32x32x16_bf16 v[48:63], v[200:203], v[156:159], v[48:63]
	ds_read_b128 v[196:199], v248 offset:9280
	v_add_u32_e32 v14, s50, v186
	v_add_u32_e32 v15, v14, v175
	v_mfma_f32_32x32x16_bf16 v[32:47], v[204:207], v[156:159], v[32:47]
	ds_read_b128 v[200:203], v248 offset:13888
	v_add_u32_e32 v14, v14, v187
	ds_write_b128 v15, v[128:131] offset:9216
	v_mfma_f32_32x32x16_bf16 v[16:31], v[208:211], v[156:159], v[16:31]
	ds_read_b128 v[204:207], v248 offset:18496
	ds_write_b128 v14, v[132:135] offset:9216
	v_mfma_f32_32x32x16_bf16 v[64:79], v[212:215], v[160:163], v[64:79]
	ds_read_b128 v[208:211], v248 offset:23104
	v_add_u32_e32 v249, s55, v190
	v_mfma_f32_32x32x16_bf16 v[48:63], v[216:219], v[160:163], v[48:63]
	ds_read_b128 v[212:215], v248 offset:9312
	v_mfma_f32_32x32x16_bf16 v[32:47], v[220:223], v[160:163], v[32:47]
	ds_read_b128 v[216:219], v248 offset:13920
	v_mfma_f32_32x32x16_bf16 v[16:31], v[224:227], v[160:163], v[16:31]
	ds_read_b128 v[220:223], v248 offset:18528
	ds_read_b128 v[224:227], v248 offset:23136
	s_waitcnt lgkmcnt(4)
	v_mfma_f32_32x32x16_bf16 v[64:79], v[196:199], v[164:167], v[64:79]
	ds_read_b128 v[196:199], v249
	s_add_i32 s0, s54, 4
	s_cmp_lt_u32 s54, s43
	v_mfma_f32_32x32x16_bf16 v[48:63], v[200:203], v[164:167], v[48:63]
	ds_read_b128 v[200:203], v249 offset:4608
	s_cselect_b32 s0, s0, s45
	s_lshl_b32 s8, s0, 6
	v_mfma_f32_32x32x16_bf16 v[32:47], v[204:207], v[164:167], v[32:47]
	ds_read_b128 v[204:207], v249 offset:32
	v_add_u32_e32 v14, s8, v174
	v_ashrrev_i32_e32 v15, 31, v14
	v_mfma_f32_32x32x16_bf16 v[16:31], v[208:211], v[164:167], v[16:31]
	ds_read_b128 v[208:211], v249 offset:4640
	v_lshlrev_b64 v[14:15], 10, v[14:15]
	v_lshl_add_u64 v[132:133], s[8:9], 1, v[176:177]
	s_waitcnt lgkmcnt(4)
	v_mfma_f32_32x32x16_bf16 v[64:79], v[212:215], v[168:171], v[64:79]
	ds_read_b128 v[212:215], v249 offset:64
	v_lshl_add_u64 v[14:15], v[182:183], 0, v[14:15]
	v_lshl_add_u64 v[128:129], v[132:133], 0, v[178:179]
	v_mfma_f32_32x32x16_bf16 v[48:63], v[216:219], v[168:171], v[48:63]
	ds_read_b128 v[216:219], v249 offset:4672
	global_load_dwordx4 v[136:139], v[14:15], off
	s_nop 0
	v_mfma_f32_32x32x16_bf16 v[32:47], v[220:223], v[168:171], v[32:47]
	ds_read_b128 v[220:223], v249 offset:96
	global_load_dwordx4 v[128:131], v[128:129], off
	v_lshl_add_u64 v[14:15], v[132:133], 0, v[180:181]
	v_mfma_f32_32x32x16_bf16 v[16:31], v[224:227], v[168:171], v[16:31]
	ds_read_b128 v[224:227], v249 offset:4704
	global_load_dwordx4 v[132:135], v[14:15], off
	v_add_u32_e32 v248, s55, v190
	s_waitcnt lgkmcnt(4)
	v_mfma_f32_32x32x16_bf16 v[80:95], v[196:199], v[232:235], v[112:127]
	ds_read_b128 v[196:199], v248 offset:9216
	v_mfma_f32_32x32x16_bf16 v[96:111], v[200:203], v[232:235], v[112:127]
	ds_read_b128 v[200:203], v248 offset:13824
	v_mfma_f32_32x32x16_bf16 v[80:95], v[204:207], v[236:239], v[80:95]
	ds_read_b128 v[204:207], v248 offset:18432
	v_mfma_f32_32x32x16_bf16 v[96:111], v[208:211], v[236:239], v[96:111]
	ds_read_b128 v[208:211], v248 offset:23040
	s_waitcnt lgkmcnt(4)
	v_mfma_f32_32x32x16_bf16 v[80:95], v[212:215], v[240:243], v[80:95]
	ds_read_b128 v[212:215], v248 offset:9248
	v_mfma_f32_32x32x16_bf16 v[96:111], v[216:219], v[240:243], v[96:111]
	ds_read_b128 v[216:219], v248 offset:13856
	v_mfma_f32_32x32x16_bf16 v[80:95], v[220:223], v[244:247], v[80:95]
	ds_read_b128 v[220:223], v248 offset:18464
	v_mfma_f32_32x32x16_bf16 v[96:111], v[224:227], v[244:247], v[96:111]
	ds_read_b128 v[224:227], v248 offset:23072
	s_setprio 0
	s_waitcnt lgkmcnt(8)
	s_barrier
	v_max3_f32 v14, v80, v81, v82
	v_max3_f32 v15, v96, v97, v98
	v_max3_f32 v14, v14, v83, v84
	v_max3_f32 v15, v15, v99, v100
	v_max3_f32 v14, v14, v85, v86
	v_max3_f32 v15, v15, v101, v102
	v_max3_f32 v14, v14, v87, v88
	v_max3_f32 v15, v15, v103, v104
	v_max3_f32 v14, v14, v89, v90
	v_max3_f32 v15, v15, v105, v106
	v_max3_f32 v14, v14, v91, v92
	v_max3_f32 v15, v15, v107, v108
	v_max_f32_e32 v140, v111, v111
	v_max_f32_e32 v141, v95, v95
	v_max3_f32 v14, v14, v93, v94
	v_max3_f32 v15, v15, v109, v110
	v_max_f32_e32 v140, v141, v140
	v_max3_f32 v14, v14, v15, v140
	v_cmp_lt_f32_e32 vcc, s33, v14
	s_cbranch_vccnz .Lfd_b_resc
.Lfd_b_exp:
	v_exp_f32_e32 v80, v80
	v_exp_f32_e32 v96, v96
	v_exp_f32_e32 v81, v81
	v_exp_f32_e32 v97, v97
	v_exp_f32_e32 v88, v88
	v_exp_f32_e32 v104, v104
	v_exp_f32_e32 v89, v89
	v_exp_f32_e32 v105, v105
	v_exp_f32_e32 v82, v82
	v_exp_f32_e32 v98, v98
	v_exp_f32_e32 v83, v83
	v_exp_f32_e32 v99, v99
	v_exp_f32_e32 v90, v90
	v_exp_f32_e32 v106, v106
	v_exp_f32_e32 v91, v91
	v_exp_f32_e32 v107, v107
	v_exp_f32_e32 v84, v84
	v_exp_f32_e32 v100, v100
	v_exp_f32_e32 v85, v85
	v_exp_f32_e32 v101, v101
	v_exp_f32_e32 v92, v92
	v_exp_f32_e32 v108, v108
	v_exp_f32_e32 v93, v93
	v_exp_f32_e32 v109, v109
	v_exp_f32_e32 v86, v86
	v_exp_f32_e32 v102, v102
	v_exp_f32_e32 v87, v87
	v_exp_f32_e32 v103, v103
	v_exp_f32_e32 v94, v94
	v_exp_f32_e32 v110, v110
	v_exp_f32_e32 v95, v95
	v_exp_f32_e32 v111, v111
	v_pk_add_f32 v[140:141], v[80:81], v[96:97]
	v_pk_add_f32 v[142:143], v[82:83], v[98:99]
	v_pk_add_f32 v[144:145], v[84:85], v[100:101]
	v_pk_add_f32 v[146:147], v[86:87], v[102:103]
	v_pk_add_f32 v[148:149], v[88:89], v[104:105]
	v_pk_add_f32 v[150:151], v[90:91], v[106:107]
	v_pk_add_f32 v[152:153], v[92:93], v[108:109]
	v_pk_add_f32 v[154:155], v[94:95], v[110:111]
	v_pk_add_f32 v[140:141], v[140:141], v[142:143]
	v_pk_add_f32 v[144:145], v[144:145], v[146:147]
	v_pk_add_f32 v[148:149], v[148:149], v[150:151]
	v_pk_add_f32 v[152:153], v[152:153], v[154:155]
	v_pk_add_f32 v[140:141], v[140:141], v[144:145]
	v_pk_add_f32 v[148:149], v[148:149], v[152:153]
	v_pk_add_f32 v[140:141], v[140:141], v[148:149]
	v_add_f32_e32 v14, v140, v141
	v_cvt_pk_bf16_f32 v140, v80, v81
	v_cvt_pk_bf16_f32 v141, v82, v83
	v_cvt_pk_bf16_f32 v142, v84, v85
	v_cvt_pk_bf16_f32 v143, v86, v87
	v_cvt_pk_bf16_f32 v144, v88, v89
	v_cvt_pk_bf16_f32 v145, v90, v91
	v_cvt_pk_bf16_f32 v146, v92, v93
	v_cvt_pk_bf16_f32 v147, v94, v95
	v_cvt_pk_bf16_f32 v148, v96, v97
	v_cvt_pk_bf16_f32 v149, v98, v99
	v_cvt_pk_bf16_f32 v150, v100, v101
	v_cvt_pk_bf16_f32 v151, v102, v103
	v_cvt_pk_bf16_f32 v152, v104, v105
	v_cvt_pk_bf16_f32 v153, v106, v107
	v_cvt_pk_bf16_f32 v154, v108, v109
	v_cvt_pk_bf16_f32 v155, v110, v111
	v_add_f32_e32 v193, v193, v14
	s_waitcnt lgkmcnt(0)
	s_barrier
	v_mfma_f32_32x32x16_bf16 v[64:79], v[196:199], v[140:143], v[64:79]
	s_setprio 1
	v_add_u32_e32 v0, s51, v188
	s_waitcnt vmcnt(5)
	ds_write_b128 v0, v[10:13]
	v_mfma_f32_32x32x16_bf16 v[48:63], v[200:203], v[140:143], v[48:63]
	ds_read_b128 v[196:199], v248 offset:9280
	v_add_u32_e32 v0, s51, v186
	v_add_u32_e32 v10, v0, v175
	v_mfma_f32_32x32x16_bf16 v[32:47], v[204:207], v[140:143], v[32:47]
	ds_read_b128 v[200:203], v248 offset:13888
	v_add_u32_e32 v0, v0, v187
	s_waitcnt vmcnt(4)
	ds_write_b128 v10, v[2:5] offset:9216
	v_mfma_f32_32x32x16_bf16 v[16:31], v[208:211], v[140:143], v[16:31]
	ds_read_b128 v[204:207], v248 offset:18496
	s_waitcnt vmcnt(3)
	ds_write_b128 v0, v[6:9] offset:9216
	v_mfma_f32_32x32x16_bf16 v[64:79], v[212:215], v[144:147], v[64:79]
	ds_read_b128 v[208:211], v248 offset:23104
	v_add_u32_e32 v249, s50, v190
	v_mfma_f32_32x32x16_bf16 v[48:63], v[216:219], v[144:147], v[48:63]
	ds_read_b128 v[212:215], v248 offset:9312
	s_add_i32 s54, s54, 2
	s_mov_b32 s0, s51
	v_mfma_f32_32x32x16_bf16 v[32:47], v[220:223], v[144:147], v[32:47]
	ds_read_b128 v[216:219], v248 offset:13920
	s_mov_b32 s51, s50
	s_mov_b32 s50, s55
	v_mfma_f32_32x32x16_bf16 v[16:31], v[224:227], v[144:147], v[16:31]
	ds_read_b128 v[220:223], v248 offset:18528
	ds_read_b128 v[224:227], v248 offset:23136
	s_mov_b32 s55, s0
	s_addk_i32 s47, 0x80
	s_waitcnt lgkmcnt(4)
	v_mfma_f32_32x32x16_bf16 v[64:79], v[196:199], v[148:151], v[64:79]
	ds_read_b128 v[196:199], v249
	s_add_i32 s1, s54, 3
	s_cmp_lt_u32 s1, s44
	v_mfma_f32_32x32x16_bf16 v[48:63], v[200:203], v[148:151], v[48:63]
	ds_read_b128 v[200:203], v249 offset:4608
	s_cselect_b32 s1, s1, s45
	s_lshl_b32 s8, s1, 6
	v_mfma_f32_32x32x16_bf16 v[32:47], v[204:207], v[148:151], v[32:47]
	ds_read_b128 v[204:207], v249 offset:32
	v_add_u32_e32 v2, s8, v174
	v_ashrrev_i32_e32 v3, 31, v2
	v_mfma_f32_32x32x16_bf16 v[16:31], v[208:211], v[148:151], v[16:31]
	ds_read_b128 v[208:211], v249 offset:4640
	v_lshlrev_b64 v[2:3], 10, v[2:3]
	v_lshl_add_u64 v[6:7], s[8:9], 1, v[176:177]
	s_waitcnt lgkmcnt(4)
	v_mfma_f32_32x32x16_bf16 v[64:79], v[212:215], v[152:155], v[64:79]
	ds_read_b128 v[212:215], v249 offset:64
	v_lshl_add_u64 v[2:3], v[182:183], 0, v[2:3]
	v_lshl_add_u64 v[4:5], v[6:7], 0, v[178:179]
	v_mfma_f32_32x32x16_bf16 v[48:63], v[216:219], v[152:155], v[48:63]
	ds_read_b128 v[216:219], v249 offset:4672
	v_lshl_add_u64 v[6:7], v[6:7], 0, v[180:181]
	global_load_dwordx4 v[10:13], v[2:3], off
	v_mfma_f32_32x32x16_bf16 v[32:47], v[220:223], v[152:155], v[32:47]
	ds_read_b128 v[220:223], v249 offset:96
	s_nop 0
	global_load_dwordx4 v[2:5], v[4:5], off
	v_mfma_f32_32x32x16_bf16 v[16:31], v[224:227], v[152:155], v[16:31]
	ds_read_b128 v[224:227], v249 offset:4704
	global_load_dwordx4 v[6:9], v[6:7], off
	v_add_u32_e32 v248, s51, v190
	s_waitcnt lgkmcnt(4)
	v_mfma_f32_32x32x16_bf16 v[80:95], v[196:199], v[232:235], v[112:127]
	ds_read_b128 v[196:199], v248 offset:9216
	v_mfma_f32_32x32x16_bf16 v[96:111], v[200:203], v[232:235], v[112:127]
	ds_read_b128 v[200:203], v248 offset:13824
	v_mfma_f32_32x32x16_bf16 v[80:95], v[204:207], v[236:239], v[80:95]
	ds_read_b128 v[204:207], v248 offset:18432
	v_mfma_f32_32x32x16_bf16 v[96:111], v[208:211], v[236:239], v[96:111]
	ds_read_b128 v[208:211], v248 offset:23040
	s_waitcnt lgkmcnt(4)
	v_mfma_f32_32x32x16_bf16 v[80:95], v[212:215], v[240:243], v[80:95]
	ds_read_b128 v[212:215], v248 offset:9248
	v_mfma_f32_32x32x16_bf16 v[96:111], v[216:219], v[240:243], v[96:111]
	ds_read_b128 v[216:219], v248 offset:13856
	s_add_i32 s4, s48, s54
	v_mfma_f32_32x32x16_bf16 v[80:95], v[220:223], v[244:247], v[80:95]
	ds_read_b128 v[220:223], v248 offset:18464
	v_mfma_f32_32x32x16_bf16 v[96:111], v[224:227], v[244:247], v[96:111]
	ds_read_b128 v[224:227], v248 offset:23072
	s_cmp_lt_i32 s4, -2
	s_setprio 0
	s_waitcnt lgkmcnt(8)
	s_barrier
	s_cbranch_scc1 .Lfd_head
	s_mov_b32 s0, s51
	s_mov_b32 s51, s55
	s_branch .LBB0_1072
